# phase 0 weight transposes through the hand-written engine (two items of loads in flight) with non-temporal hints on all once-read input loads
# speedup vs baseline: 1.0072x; 1.0024x over previous
.Ltr_dec:
	s_mul_i32 s37, s8, s9
	s_lshl_b32 s6, s6, 2
	s_add_u32 s37, s37, s6
	s_add_u32 s10, s10, s37
	s_addc_u32 s11, s11, 0
	s_lshl_b32 s37, s9, 5
	s_add_u32 s88, s10, s37
	s_addc_u32 s89, s11, 0
	v_mul_lo_u32 v46, v41, s9
	v_add_u32_e32 v46, v46, v42
	s_mul_i32 s37, s7, s48
	s_lshl_b32 s6, s8, 1
	s_add_u32 s37, s37, s6
	s_add_u32 s36, s36, s37
	s_addc_u32 s37, 0, 0
	s_add_u32 s36, s74, s36
	s_addc_u32 s37, s75, s37
	v_mul_lo_u32 v94, v44, s48
	v_add_u32_e32 v94, v94, v45
	v_mov_b32_e32 v92, s36
	v_mov_b32_e32 v93, s37
	v_lshl_add_u64 v[92:93], v[92:93], 0, v[94:95]
	s_cmp_eq_u32 s49, 0
	s_cbranch_scc0 .Ltr_ld1
	global_load_dwordx4 v[60:63], v46, s[10:11] nt
	global_load_dwordx4 v[64:67], v46, s[88:89] nt
	v_mov_b32_e32 v84, v92
	v_mov_b32_e32 v85, v93
	s_branch .Ltr_ldone
.Ltr_ld1:
	s_cmp_eq_u32 s49, 1
	s_cbranch_scc0 .Ltr_ld2
	global_load_dwordx4 v[68:71], v46, s[10:11] nt
	global_load_dwordx4 v[72:75], v46, s[88:89] nt
	v_mov_b32_e32 v86, v92
	v_mov_b32_e32 v87, v93
	s_branch .Ltr_ldone
.Ltr_ld2:
	global_load_dwordx4 v[76:79], v46, s[10:11] nt
	global_load_dwordx4 v[80:83], v46, s[88:89] nt
	v_mov_b32_e32 v88, v92
	v_mov_b32_e32 v89, v93
